# A-in epilogue: the 112 neighbour exchanges per unit done with DPP moves (row_shr:1/2, row_newbcast:15/14) instead of ds_bpermute
# speedup vs baseline: 1.0014x; 1.0014x over previous
.LBB0_124:
	v_lshl_or_b32 v158, s62, 6, v162
	v_ashrrev_i32_e32 v159, 31, v158
	v_lshlrev_b64 v[40:41], 2, v[158:159]
	v_lshl_add_u64 v[42:43], s[24:25], 0, v[40:41]
	flat_load_dwordx4 v[44:47], v[42:43]
	v_lshl_add_u64 v[42:43], s[44:45], 0, v[40:41]
	v_lshl_add_u64 v[40:41], s[46:47], 0, v[40:41]
	flat_load_dwordx4 v[48:51], v[42:43]
	s_nop 0
	flat_load_dwordx4 v[40:43], v[40:41]
	v_mul_f32_e32 v140, 0xbfb8aa3b, v124
	v_mul_f32_e32 v141, 0xbfb8aa3b, v125
	v_exp_f32_e32 v140, v140
	v_exp_f32_e32 v141, v141
	v_pk_mul_f32 v[132:133], v[136:137], v[132:133]
	s_lshl_b32 s51, s60, 8
	s_nop 1
	v_mov_b32_dpp v136, v132 row_shr:1 row_mask:0xf bank_mask:0xf
	v_pk_add_f32 v[142:143], v[140:141], 1.0 op_sel_hi:[1,0]
	s_nop 1
	v_mov_b32_dpp v137, v132 row_shr:2 row_mask:0xf bank_mask:0xf
	v_div_scale_f32 v141, s[60:61], v143, v143, v125
	v_rcp_f32_e32 v148, v141
	s_waitcnt lgkmcnt(0)
	v_cndmask_b32_e64 v140, v136, 0, s[4:5]
	v_cndmask_b32_e64 v136, 0, v137, s[42:43]
	v_pk_mul_f32 v[134:135], v[138:139], v[134:135]
	v_fma_f32 v137, -v141, v148, 1.0
	v_fmac_f32_e32 v148, v137, v148
	v_div_scale_f32 v137, vcc, v125, v143, v125
	v_mul_f32_e32 v138, v137, v148
	v_fma_f32 v139, -v141, v138, v137
	v_fmac_f32_e32 v138, v139, v148
	v_div_scale_f32 v139, s[60:61], v142, v142, v124
	v_fma_f32 v137, -v141, v138, v137
	v_rcp_f32_e32 v141, v139
	v_div_fmas_f32 v137, v137, v148, v138
	v_div_fixup_f32 v125, v137, v143, v125
	s_add_i32 s51, s51, s75
	v_fma_f32 v137, -v139, v141, 1.0
	v_fmac_f32_e32 v141, v137, v141
	v_div_scale_f32 v137, vcc, v124, v142, v124
	v_mul_f32_e32 v138, v137, v141
	v_fma_f32 v143, -v139, v138, v137
	v_fmac_f32_e32 v138, v143, v141
	v_fma_f32 v137, -v139, v138, v137
	v_div_fmas_f32 v137, v137, v141, v138
	v_div_fixup_f32 v124, v137, v142, v124
	v_pk_mul_f32 v[124:125], v[128:129], v[124:125]
	v_mul_f32_e32 v128, 0xbfb8aa3b, v126
	v_mul_f32_e32 v129, 0xbfb8aa3b, v127
	v_exp_f32_e32 v128, v128
	v_exp_f32_e32 v129, v129
	s_nop 1
	v_mov_b32_dpp v139, v134 row_shr:1 row_mask:0xf bank_mask:0xf
	s_nop 1
	v_mov_b32_dpp v137, v133 row_shr:1 row_mask:0xf bank_mask:0xf
	s_nop 1
	v_mov_b32_dpp v138, v133 row_shr:2 row_mask:0xf bank_mask:0xf
	v_pk_add_f32 v[128:129], v[128:129], 1.0 op_sel_hi:[1,0]
	s_nop 1
	v_mov_b32_dpp v143, v134 row_shr:2 row_mask:0xf bank_mask:0xf
	v_div_scale_f32 v148, s[60:61], v129, v129, v127
	v_rcp_f32_e32 v171, v148
	s_waitcnt lgkmcnt(0)
	v_cndmask_b32_e64 v142, v139, 0, s[4:5]
	v_cndmask_b32_e64 v141, v137, 0, s[4:5]
	v_cndmask_b32_e64 v137, 0, v138, s[42:43]
	v_fma_f32 v139, -v148, v171, 1.0
	v_fmac_f32_e32 v171, v139, v171
	v_div_scale_f32 v139, vcc, v127, v129, v127
	v_cndmask_b32_e64 v138, 0, v143, s[42:43]
	v_mul_f32_e32 v143, v139, v171
	v_fma_f32 v172, -v148, v143, v139
	v_fmac_f32_e32 v143, v172, v171
	v_fma_f32 v139, -v148, v143, v139
	v_div_scale_f32 v148, s[60:61], v128, v128, v126
	v_rcp_f32_e32 v172, v148
	v_div_fmas_f32 v139, v139, v171, v143
	v_div_fixup_f32 v127, v139, v129, v127
	v_fma_f32 v129, -v148, v172, 1.0
	v_fmac_f32_e32 v172, v129, v172
	v_div_scale_f32 v129, vcc, v126, v128, v126
	v_mul_f32_e32 v139, v129, v172
	v_fma_f32 v143, -v148, v139, v129
	v_fmac_f32_e32 v139, v143, v172
	v_fma_f32 v129, -v148, v139, v129
	s_nop 1
	v_mov_b32_dpp v143, v135 row_shr:1 row_mask:0xf bank_mask:0xf
	s_nop 1
	v_mov_b32_dpp v148, v135 row_shr:2 row_mask:0xf bank_mask:0xf
	v_div_fmas_f32 v129, v129, v172, v139
	v_div_fixup_f32 v126, v129, v128, v126
	v_or_b32_e32 v128, s51, v160
	v_pk_mul_f32 v[126:127], v[130:131], v[126:127]
	s_waitcnt lgkmcnt(0)
	v_cndmask_b32_e64 v143, v143, 0, s[4:5]
	v_cndmask_b32_e64 v139, 0, v148, s[42:43]
	v_cmp_gt_i32_e32 vcc, s74, v128
	s_and_saveexec_b64 s[62:63], vcc
	s_xor_b64 s[62:63], exec, s[62:63]
	s_cbranch_execnz .LBB0_201
	s_or_saveexec_b64 s[62:63], s[62:63]
	v_mov_b64_e32 v[130:131], 0
	s_xor_b64 exec, exec, s[62:63]
	s_cbranch_execnz .LBB0_210

.LBB0_129:
	s_or_b64 exec, exec, s[60:61]
	v_pk_mul_f32 v[116:117], v[120:121], v[116:117]
	s_nop 1
	v_mov_b32_dpp v125, v132 row_newbcast:15 row_mask:0xf bank_mask:0xf
	s_nop 1
	v_mov_b32_dpp v120, v132 row_newbcast:14 row_mask:0xf bank_mask:0xf
	v_pk_mul_f32 v[118:119], v[122:123], v[118:119]
	s_nop 1
	v_mov_b32_dpp v121, v116 row_shr:2 row_mask:0xf bank_mask:0xf
	s_nop 1
	v_mov_b32_dpp v126, v133 row_newbcast:15 row_mask:0xf bank_mask:0xf
	s_nop 1
	v_mov_b32_dpp v122, v133 row_newbcast:14 row_mask:0xf bank_mask:0xf
	s_nop 1
	v_mov_b32_dpp v123, v117 row_shr:2 row_mask:0xf bank_mask:0xf
	s_waitcnt lgkmcnt(0)
	v_cndmask_b32_e64 v120, v120, v125, s[6:7]
	v_cndmask_b32_e64 v120, v120, v121, s[42:43]
	s_nop 1
	v_mov_b32_dpp v131, v134 row_newbcast:15 row_mask:0xf bank_mask:0xf
	v_cndmask_b32_e64 v121, v122, v126, s[6:7]
	s_nop 1
	v_mov_b32_dpp v122, v134 row_newbcast:14 row_mask:0xf bank_mask:0xf
	v_cndmask_b32_e64 v121, v121, v123, s[42:43]
	s_nop 1
	v_mov_b32_dpp v123, v118 row_shr:2 row_mask:0xf bank_mask:0xf
	s_nop 1
	v_mov_b32_dpp v132, v135 row_newbcast:15 row_mask:0xf bank_mask:0xf
	s_nop 1
	v_mov_b32_dpp v130, v135 row_newbcast:14 row_mask:0xf bank_mask:0xf
	s_nop 1
	v_mov_b32_dpp v134, v119 row_shr:2 row_mask:0xf bank_mask:0xf
	s_nop 1
	v_mov_b32_dpp v124, v116 row_shr:1 row_mask:0xf bank_mask:0xf
	s_nop 1
	v_mov_b32_dpp v127, v117 row_shr:1 row_mask:0xf bank_mask:0xf
	s_nop 1
	v_mov_b32_dpp v129, v118 row_shr:1 row_mask:0xf bank_mask:0xf
	s_nop 1
	v_mov_b32_dpp v133, v119 row_shr:1 row_mask:0xf bank_mask:0xf
	s_waitcnt lgkmcnt(0)
	v_cndmask_b32_e64 v122, v122, v131, s[6:7]
	v_cndmask_b32_e64 v122, v122, v123, s[42:43]
	v_cndmask_b32_e64 v123, v130, v132, s[6:7]
	v_or_b32_e32 v130, 16, v128
	v_cndmask_b32_e64 v123, v123, v134, s[42:43]
	v_cmp_gt_i32_e32 vcc, s74, v130
	s_and_saveexec_b64 s[60:61], vcc
	s_xor_b64 s[60:61], exec, s[60:61]
	s_cbranch_execz .LBB0_131
	v_cvt_pk_bf16_f32 v134, v116, v117
	s_nop 0
	v_cvt_pk_bf16_f32 v134, v118, v119

.LBB0_139:
	s_or_b64 exec, exec, s[60:61]
	v_pk_mul_f32 v[100:101], v[104:105], v[100:101]
	s_nop 1
	v_mov_b32_dpp v109, v116 row_newbcast:15 row_mask:0xf bank_mask:0xf
	s_nop 1
	v_mov_b32_dpp v104, v116 row_newbcast:14 row_mask:0xf bank_mask:0xf
	v_pk_mul_f32 v[102:103], v[106:107], v[102:103]
	s_nop 1
	v_mov_b32_dpp v105, v100 row_shr:2 row_mask:0xf bank_mask:0xf
	s_nop 1
	v_mov_b32_dpp v110, v117 row_newbcast:15 row_mask:0xf bank_mask:0xf
	s_nop 1
	v_mov_b32_dpp v106, v117 row_newbcast:14 row_mask:0xf bank_mask:0xf
	s_nop 1
	v_mov_b32_dpp v107, v101 row_shr:2 row_mask:0xf bank_mask:0xf
	s_waitcnt lgkmcnt(0)
	v_cndmask_b32_e64 v104, v104, v109, s[6:7]
	v_cndmask_b32_e64 v104, v104, v105, s[42:43]
	s_nop 1
	v_mov_b32_dpp v114, v118 row_newbcast:15 row_mask:0xf bank_mask:0xf
	v_cndmask_b32_e64 v105, v106, v110, s[6:7]
	s_nop 1
	v_mov_b32_dpp v106, v118 row_newbcast:14 row_mask:0xf bank_mask:0xf
	v_cndmask_b32_e64 v105, v105, v107, s[42:43]
	s_nop 1
	v_mov_b32_dpp v107, v102 row_shr:2 row_mask:0xf bank_mask:0xf
	s_nop 1
	v_mov_b32_dpp v115, v119 row_newbcast:15 row_mask:0xf bank_mask:0xf
	s_nop 1
	v_mov_b32_dpp v112, v119 row_newbcast:14 row_mask:0xf bank_mask:0xf
	s_nop 1
	v_mov_b32_dpp v117, v103 row_shr:2 row_mask:0xf bank_mask:0xf
	s_nop 1
	v_mov_b32_dpp v108, v100 row_shr:1 row_mask:0xf bank_mask:0xf
	s_nop 1
	v_mov_b32_dpp v111, v101 row_shr:1 row_mask:0xf bank_mask:0xf
	s_nop 1
	v_mov_b32_dpp v113, v102 row_shr:1 row_mask:0xf bank_mask:0xf
	s_nop 1
	v_mov_b32_dpp v116, v103 row_shr:1 row_mask:0xf bank_mask:0xf
	s_waitcnt lgkmcnt(0)
	v_cndmask_b32_e64 v106, v106, v114, s[6:7]
	v_cndmask_b32_e64 v106, v106, v107, s[42:43]
	v_cndmask_b32_e64 v107, v112, v115, s[6:7]
	v_or_b32_e32 v112, 32, v128
	v_cndmask_b32_e64 v107, v107, v117, s[42:43]
	v_cmp_gt_i32_e32 vcc, s74, v112
	s_and_saveexec_b64 s[60:61], vcc
	s_xor_b64 s[60:61], exec, s[60:61]
	s_cbranch_execz .LBB0_141
	v_cvt_pk_bf16_f32 v117, v100, v101
	s_nop 0
	v_cvt_pk_bf16_f32 v117, v102, v103

.LBB0_149:
	s_or_b64 exec, exec, s[60:61]
	v_pk_mul_f32 v[84:85], v[88:89], v[84:85]
	s_nop 1
	v_mov_b32_dpp v95, v100 row_newbcast:15 row_mask:0xf bank_mask:0xf
	s_nop 1
	v_mov_b32_dpp v88, v100 row_newbcast:14 row_mask:0xf bank_mask:0xf
	v_pk_mul_f32 v[86:87], v[90:91], v[86:87]
	s_nop 1
	v_mov_b32_dpp v89, v84 row_shr:2 row_mask:0xf bank_mask:0xf
	s_nop 1
	v_mov_b32_dpp v100, v101 row_newbcast:15 row_mask:0xf bank_mask:0xf
	s_nop 1
	v_mov_b32_dpp v90, v101 row_newbcast:14 row_mask:0xf bank_mask:0xf
	s_nop 1
	v_mov_b32_dpp v91, v85 row_shr:2 row_mask:0xf bank_mask:0xf
	s_waitcnt lgkmcnt(0)
	v_cndmask_b32_e64 v88, v88, v95, s[6:7]
	v_cndmask_b32_e64 v88, v88, v89, s[42:43]
	s_nop 1
	v_mov_b32_dpp v105, v102 row_newbcast:15 row_mask:0xf bank_mask:0xf
	v_cndmask_b32_e64 v89, v90, v100, s[6:7]
	s_nop 1
	v_mov_b32_dpp v90, v102 row_newbcast:14 row_mask:0xf bank_mask:0xf
	v_cndmask_b32_e64 v89, v89, v91, s[42:43]
	s_nop 1
	v_mov_b32_dpp v91, v86 row_shr:2 row_mask:0xf bank_mask:0xf
	s_nop 1
	v_mov_b32_dpp v102, v103 row_newbcast:15 row_mask:0xf bank_mask:0xf
	s_nop 1
	v_mov_b32_dpp v92, v103 row_newbcast:14 row_mask:0xf bank_mask:0xf
	s_nop 1
	v_mov_b32_dpp v93, v87 row_shr:2 row_mask:0xf bank_mask:0xf
	s_nop 1
	v_mov_b32_dpp v94, v84 row_shr:1 row_mask:0xf bank_mask:0xf
	s_nop 1
	v_mov_b32_dpp v101, v85 row_shr:1 row_mask:0xf bank_mask:0xf
	s_nop 1
	v_mov_b32_dpp v104, v86 row_shr:1 row_mask:0xf bank_mask:0xf
	s_nop 1
	v_mov_b32_dpp v103, v87 row_shr:1 row_mask:0xf bank_mask:0xf
	s_waitcnt lgkmcnt(0)
	v_cndmask_b32_e64 v90, v90, v105, s[6:7]
	v_cndmask_b32_e64 v90, v90, v91, s[42:43]
	v_cndmask_b32_e64 v91, v92, v102, s[6:7]
	v_or_b32_e32 v96, 48, v128
	v_cndmask_b32_e64 v91, v91, v93, s[42:43]
	v_cmp_gt_i32_e32 vcc, s74, v96
	s_and_saveexec_b64 s[60:61], vcc
	s_xor_b64 s[60:61], exec, s[60:61]
	s_cbranch_execz .LBB0_153
	v_and_b32_e32 v98, 0x7ff, v96
	v_cmp_lt_u32_e32 vcc, s83, v98
	v_cvt_pk_bf16_f32 v92, v84, v85
	v_cvt_pk_bf16_f32 v93, v86, v87
	s_and_saveexec_b64 s[62:63], s[8:9]
	s_cbranch_execz .LBB0_152
	v_ashrrev_i32_e32 v97, 31, v96
	v_lshlrev_b64 v[106:107], 12, v[96:97]
	v_lshl_add_u64 v[106:107], s[30:31], 0, v[106:107]
	v_lshl_add_u64 v[106:107], v[158:159], 1, v[106:107]
	flat_store_dwordx2 v[106:107], v[92:93]

.LBB0_161:
	s_or_b64 exec, exec, s[60:61]
	v_mul_f32_e32 v76, 0xbfb8aa3b, v60
	v_mul_f32_e32 v77, 0xbfb8aa3b, v61
	v_exp_f32_e32 v76, v76
	v_exp_f32_e32 v77, v77
	v_pk_mul_f32 v[68:69], v[72:73], v[68:69]
	s_nop 1
	v_mov_b32_dpp v72, v68 row_shr:1 row_mask:0xf bank_mask:0xf
	s_nop 1
	v_mov_b32_dpp v73, v68 row_shr:2 row_mask:0xf bank_mask:0xf
	v_pk_add_f32 v[78:79], v[76:77], 1.0 op_sel_hi:[1,0]
	v_pk_mul_f32 v[70:71], v[74:75], v[70:71]
	v_div_scale_f32 v77, s[60:61], v79, v79, v61
	v_rcp_f32_e32 v80, v77
	s_waitcnt lgkmcnt(0)
	v_cndmask_b32_e64 v76, v72, 0, s[4:5]
	v_cndmask_b32_e64 v72, 0, v73, s[42:43]
	s_addk_i32 s51, 0x80
	v_fma_f32 v73, -v77, v80, 1.0
	v_fmac_f32_e32 v80, v73, v80
	v_div_scale_f32 v73, vcc, v61, v79, v61
	v_mul_f32_e32 v74, v73, v80
	v_fma_f32 v75, -v77, v74, v73
	v_fmac_f32_e32 v74, v75, v80
	v_div_scale_f32 v75, s[60:61], v78, v78, v60
	v_fma_f32 v73, -v77, v74, v73
	v_rcp_f32_e32 v77, v75
	v_div_fmas_f32 v73, v73, v80, v74
	v_div_fixup_f32 v61, v73, v79, v61
	v_fma_f32 v73, -v75, v77, 1.0
	v_fmac_f32_e32 v77, v73, v77
	v_div_scale_f32 v73, vcc, v60, v78, v60
	v_mul_f32_e32 v74, v73, v77
	v_fma_f32 v79, -v75, v74, v73
	v_fmac_f32_e32 v74, v79, v77
	v_fma_f32 v73, -v75, v74, v73
	v_div_fmas_f32 v73, v73, v77, v74
	v_div_fixup_f32 v60, v73, v78, v60
	v_pk_mul_f32 v[60:61], v[64:65], v[60:61]
	v_mul_f32_e32 v64, 0xbfb8aa3b, v62
	v_mul_f32_e32 v65, 0xbfb8aa3b, v63
	v_exp_f32_e32 v64, v64
	v_exp_f32_e32 v65, v65
	s_nop 1
	v_mov_b32_dpp v75, v70 row_shr:1 row_mask:0xf bank_mask:0xf
	s_nop 1
	v_mov_b32_dpp v73, v69 row_shr:1 row_mask:0xf bank_mask:0xf
	s_nop 1
	v_mov_b32_dpp v74, v69 row_shr:2 row_mask:0xf bank_mask:0xf
	v_pk_add_f32 v[64:65], v[64:65], 1.0 op_sel_hi:[1,0]
	s_nop 1
	v_mov_b32_dpp v79, v70 row_shr:2 row_mask:0xf bank_mask:0xf
	v_div_scale_f32 v80, s[60:61], v65, v65, v63
	v_rcp_f32_e32 v81, v80
	s_waitcnt lgkmcnt(0)
	v_cndmask_b32_e64 v78, v75, 0, s[4:5]
	v_cndmask_b32_e64 v77, v73, 0, s[4:5]
	v_cndmask_b32_e64 v73, 0, v74, s[42:43]
	v_fma_f32 v75, -v80, v81, 1.0
	v_fmac_f32_e32 v81, v75, v81
	v_div_scale_f32 v75, vcc, v63, v65, v63
	v_cndmask_b32_e64 v74, 0, v79, s[42:43]
	v_mul_f32_e32 v79, v75, v81
	v_fma_f32 v82, -v80, v79, v75
	v_fmac_f32_e32 v79, v82, v81
	v_fma_f32 v75, -v80, v79, v75
	v_div_scale_f32 v80, s[60:61], v64, v64, v62
	v_rcp_f32_e32 v82, v80
	v_div_fmas_f32 v75, v75, v81, v79
	v_div_fixup_f32 v63, v75, v65, v63
	v_fma_f32 v65, -v80, v82, 1.0
	v_fmac_f32_e32 v82, v65, v82
	v_div_scale_f32 v65, vcc, v62, v64, v62
	v_mul_f32_e32 v75, v65, v82
	v_fma_f32 v79, -v80, v75, v65
	v_fmac_f32_e32 v75, v79, v82
	v_fma_f32 v65, -v80, v75, v65
	s_nop 1
	v_mov_b32_dpp v79, v71 row_shr:1 row_mask:0xf bank_mask:0xf
	s_nop 1
	v_mov_b32_dpp v80, v71 row_shr:2 row_mask:0xf bank_mask:0xf
	v_div_fmas_f32 v65, v65, v82, v75
	v_div_fixup_f32 v62, v65, v64, v62
	v_or_b32_e32 v64, s51, v160
	v_pk_mul_f32 v[62:63], v[66:67], v[62:63]
	s_waitcnt lgkmcnt(0)
	v_cndmask_b32_e64 v79, v79, 0, s[4:5]
	v_cndmask_b32_e64 v75, 0, v80, s[42:43]
	v_cmp_gt_i32_e32 vcc, s74, v64
	s_and_saveexec_b64 s[62:63], vcc
	s_xor_b64 s[62:63], exec, s[62:63]
	s_cbranch_execnz .LBB0_216
	s_or_saveexec_b64 s[62:63], s[62:63]
	v_mov_b64_e32 v[66:67], 0
	s_xor_b64 exec, exec, s[62:63]
	s_cbranch_execnz .LBB0_225

.LBB0_166:
	s_or_b64 exec, exec, s[60:61]
	v_pk_mul_f32 v[52:53], v[56:57], v[52:53]
	s_nop 1
	v_mov_b32_dpp v61, v68 row_newbcast:15 row_mask:0xf bank_mask:0xf
	s_nop 1
	v_mov_b32_dpp v56, v68 row_newbcast:14 row_mask:0xf bank_mask:0xf
	v_pk_mul_f32 v[54:55], v[58:59], v[54:55]
	s_nop 1
	v_mov_b32_dpp v57, v52 row_shr:2 row_mask:0xf bank_mask:0xf
	s_nop 1
	v_mov_b32_dpp v62, v69 row_newbcast:15 row_mask:0xf bank_mask:0xf
	s_nop 1
	v_mov_b32_dpp v58, v69 row_newbcast:14 row_mask:0xf bank_mask:0xf
	s_nop 1
	v_mov_b32_dpp v59, v53 row_shr:2 row_mask:0xf bank_mask:0xf
	s_waitcnt lgkmcnt(0)
	v_cndmask_b32_e64 v56, v56, v61, s[6:7]
	v_cndmask_b32_e64 v56, v56, v57, s[42:43]
	s_nop 1
	v_mov_b32_dpp v67, v70 row_newbcast:15 row_mask:0xf bank_mask:0xf
	v_cndmask_b32_e64 v57, v58, v62, s[6:7]
	s_nop 1
	v_mov_b32_dpp v58, v70 row_newbcast:14 row_mask:0xf bank_mask:0xf
	v_cndmask_b32_e64 v57, v57, v59, s[42:43]
	s_nop 1
	v_mov_b32_dpp v59, v54 row_shr:2 row_mask:0xf bank_mask:0xf
	s_nop 1
	v_mov_b32_dpp v68, v71 row_newbcast:15 row_mask:0xf bank_mask:0xf
	s_nop 1
	v_mov_b32_dpp v66, v71 row_newbcast:14 row_mask:0xf bank_mask:0xf
	s_nop 1
	v_mov_b32_dpp v70, v55 row_shr:2 row_mask:0xf bank_mask:0xf
	s_nop 1
	v_mov_b32_dpp v60, v52 row_shr:1 row_mask:0xf bank_mask:0xf
	s_nop 1
	v_mov_b32_dpp v63, v53 row_shr:1 row_mask:0xf bank_mask:0xf
	s_nop 1
	v_mov_b32_dpp v65, v54 row_shr:1 row_mask:0xf bank_mask:0xf
	s_nop 1
	v_mov_b32_dpp v69, v55 row_shr:1 row_mask:0xf bank_mask:0xf
	s_waitcnt lgkmcnt(0)
	v_cndmask_b32_e64 v58, v58, v67, s[6:7]
	v_cndmask_b32_e64 v58, v58, v59, s[42:43]
	v_cndmask_b32_e64 v59, v66, v68, s[6:7]
	v_or_b32_e32 v66, 16, v64
	v_cndmask_b32_e64 v59, v59, v70, s[42:43]
	v_cmp_gt_i32_e32 vcc, s74, v66
	s_and_saveexec_b64 s[60:61], vcc
	s_xor_b64 s[60:61], exec, s[60:61]
	s_cbranch_execz .LBB0_168
	v_cvt_pk_bf16_f32 v70, v52, v53
	s_nop 0
	v_cvt_pk_bf16_f32 v70, v54, v55

.LBB0_176:
	s_or_b64 exec, exec, s[60:61]
	v_pk_mul_f32 v[24:25], v[28:29], v[24:25]
	s_nop 1
	v_mov_b32_dpp v33, v52 row_newbcast:15 row_mask:0xf bank_mask:0xf
	s_nop 1
	v_mov_b32_dpp v28, v52 row_newbcast:14 row_mask:0xf bank_mask:0xf
	v_pk_mul_f32 v[26:27], v[30:31], v[26:27]
	s_nop 1
	v_mov_b32_dpp v29, v24 row_shr:2 row_mask:0xf bank_mask:0xf
	s_nop 1
	v_mov_b32_dpp v34, v53 row_newbcast:15 row_mask:0xf bank_mask:0xf
	s_nop 1
	v_mov_b32_dpp v30, v53 row_newbcast:14 row_mask:0xf bank_mask:0xf
	s_nop 1
	v_mov_b32_dpp v31, v25 row_shr:2 row_mask:0xf bank_mask:0xf
	s_waitcnt lgkmcnt(0)
	v_cndmask_b32_e64 v28, v28, v33, s[6:7]
	v_cndmask_b32_e64 v28, v28, v29, s[42:43]
	s_nop 1
	v_mov_b32_dpp v38, v54 row_newbcast:15 row_mask:0xf bank_mask:0xf
	v_cndmask_b32_e64 v29, v30, v34, s[6:7]
	s_nop 1
	v_mov_b32_dpp v30, v54 row_newbcast:14 row_mask:0xf bank_mask:0xf
	v_cndmask_b32_e64 v29, v29, v31, s[42:43]
	s_nop 1
	v_mov_b32_dpp v31, v26 row_shr:2 row_mask:0xf bank_mask:0xf
	s_nop 1
	v_mov_b32_dpp v39, v55 row_newbcast:15 row_mask:0xf bank_mask:0xf
	s_nop 1
	v_mov_b32_dpp v36, v55 row_newbcast:14 row_mask:0xf bank_mask:0xf
	s_nop 1
	v_mov_b32_dpp v53, v27 row_shr:2 row_mask:0xf bank_mask:0xf
	s_nop 1
	v_mov_b32_dpp v32, v24 row_shr:1 row_mask:0xf bank_mask:0xf
	s_nop 1
	v_mov_b32_dpp v35, v25 row_shr:1 row_mask:0xf bank_mask:0xf
	s_nop 1
	v_mov_b32_dpp v37, v26 row_shr:1 row_mask:0xf bank_mask:0xf
	s_nop 1
	v_mov_b32_dpp v52, v27 row_shr:1 row_mask:0xf bank_mask:0xf
	s_waitcnt lgkmcnt(0)
	v_cndmask_b32_e64 v30, v30, v38, s[6:7]
	v_cndmask_b32_e64 v30, v30, v31, s[42:43]
	v_cndmask_b32_e64 v31, v36, v39, s[6:7]
	v_or_b32_e32 v36, 32, v64
	v_cndmask_b32_e64 v31, v31, v53, s[42:43]
	v_cmp_gt_i32_e32 vcc, s74, v36
	s_and_saveexec_b64 s[60:61], vcc
	s_xor_b64 s[60:61], exec, s[60:61]
	s_cbranch_execz .LBB0_178
	v_cvt_pk_bf16_f32 v53, v24, v25
	s_nop 0
	v_cvt_pk_bf16_f32 v53, v26, v27

.LBB0_186:
	s_or_b64 exec, exec, s[60:61]
	v_pk_mul_f32 v[8:9], v[12:13], v[8:9]
	s_nop 1
	v_mov_b32_dpp v19, v24 row_newbcast:15 row_mask:0xf bank_mask:0xf
	s_nop 1
	v_mov_b32_dpp v12, v24 row_newbcast:14 row_mask:0xf bank_mask:0xf
	v_pk_mul_f32 v[10:11], v[14:15], v[10:11]
	s_nop 1
	v_mov_b32_dpp v13, v8 row_shr:2 row_mask:0xf bank_mask:0xf
	s_nop 1
	v_mov_b32_dpp v24, v25 row_newbcast:15 row_mask:0xf bank_mask:0xf
	s_nop 1
	v_mov_b32_dpp v14, v25 row_newbcast:14 row_mask:0xf bank_mask:0xf
	s_nop 1
	v_mov_b32_dpp v15, v9 row_shr:2 row_mask:0xf bank_mask:0xf
	s_waitcnt lgkmcnt(0)
	v_cndmask_b32_e64 v12, v12, v19, s[6:7]
	v_cndmask_b32_e64 v12, v12, v13, s[42:43]
	s_nop 1
	v_mov_b32_dpp v29, v26 row_newbcast:15 row_mask:0xf bank_mask:0xf
	v_cndmask_b32_e64 v13, v14, v24, s[6:7]
	s_nop 1
	v_mov_b32_dpp v14, v26 row_newbcast:14 row_mask:0xf bank_mask:0xf
	v_cndmask_b32_e64 v13, v13, v15, s[42:43]
	s_nop 1
	v_mov_b32_dpp v15, v10 row_shr:2 row_mask:0xf bank_mask:0xf
	s_nop 1
	v_mov_b32_dpp v26, v27 row_newbcast:15 row_mask:0xf bank_mask:0xf
	s_nop 1
	v_mov_b32_dpp v16, v27 row_newbcast:14 row_mask:0xf bank_mask:0xf
	s_nop 1
	v_mov_b32_dpp v17, v11 row_shr:2 row_mask:0xf bank_mask:0xf
	s_nop 1
	v_mov_b32_dpp v18, v8 row_shr:1 row_mask:0xf bank_mask:0xf
	s_nop 1
	v_mov_b32_dpp v25, v9 row_shr:1 row_mask:0xf bank_mask:0xf
	s_nop 1
	v_mov_b32_dpp v28, v10 row_shr:1 row_mask:0xf bank_mask:0xf
	s_nop 1
	v_mov_b32_dpp v27, v11 row_shr:1 row_mask:0xf bank_mask:0xf
	s_waitcnt lgkmcnt(0)
	v_cndmask_b32_e64 v14, v14, v29, s[6:7]
	v_cndmask_b32_e64 v14, v14, v15, s[42:43]
	v_cndmask_b32_e64 v15, v16, v26, s[6:7]
	v_or_b32_e32 v20, 48, v64
	v_cndmask_b32_e64 v15, v15, v17, s[42:43]
	v_cmp_gt_i32_e32 vcc, s74, v20
	s_and_saveexec_b64 s[60:61], vcc
	s_xor_b64 s[60:61], exec, s[60:61]
	s_cbranch_execz .LBB0_190
	v_and_b32_e32 v22, 0x7ff, v20
	v_cmp_lt_u32_e32 vcc, s83, v22
	v_cvt_pk_bf16_f32 v16, v8, v9
	v_cvt_pk_bf16_f32 v17, v10, v11
	s_and_saveexec_b64 s[62:63], s[8:9]
	s_cbranch_execz .LBB0_189
	v_ashrrev_i32_e32 v21, 31, v20
	v_lshlrev_b64 v[30:31], 12, v[20:21]
	v_lshl_add_u64 v[30:31], s[30:31], 0, v[30:31]
	v_lshl_add_u64 v[30:31], v[158:159], 1, v[30:31]
	flat_store_dwordx2 v[30:31], v[16:17]
